# same-XCC seams use a flag barrier (per-WG generation slot in one 128B line per XCC, one 32-lane sc1 poll) instead of counter+leader
# baseline (speedup 1.0000x reference)
.LBB0_8:
	s_or_b64 exec, exec, s[2:3]
	s_waitcnt lgkmcnt(0)
	s_barrier
	s_load_dwordx2 s[44:45], s[0:1], 0xd8
	s_waitcnt lgkmcnt(0)
	s_cmp_ge_i32 s44, s45
	s_cbranch_scc1 .LBB0_864
	s_load_dword s2, s[0:1], 0xe0
	s_lshl_b32 s64, s33, 3
	s_load_dwordx2 s[0:1], s[0:1], 0xc8
	s_lshl_b32 s28, s33, 9
	v_lshrrev_b32_e32 v2, 20, v0
	s_waitcnt lgkmcnt(0)
	s_cmp_lg_u32 s2, 0
	s_cselect_b64 s[30:31], -1, 0
	v_writelane_b32 v253, s0, 5
	s_add_i32 s26, s44, 1
	v_lshrrev_b32_e32 v0, 10, v0
	v_writelane_b32 v253, s1, 6
	s_and_b32 s0, s33, 7
	s_cmp_eq_u32 s0, 0
	s_cselect_b64 s[0:1], -1, 0
	v_writelane_b32 v253, s0, 7
	s_ashr_i32 s53, s33, 31
	v_or_b32_e32 v0, v0, v2
	v_writelane_b32 v253, s1, 8
	s_lshr_b32 s0, s53, 29
	s_add_i32 s0, s33, s0
	s_ashr_i32 s0, s0, 3
	s_cmpk_lg_i32 s33, 0x100
	v_writelane_b32 v253, s0, 9
	s_cselect_b64 s[0:1], -1, 0
	v_writelane_b32 v253, s0, 10
	v_mov_b32_e32 v145, 0
	v_mov_b32_e32 v247, 0x358637bd
	v_writelane_b32 v253, s1, 11
	s_add_u32 s0, s78, 0xdc00000
	s_addc_u32 s1, s79, 0
	v_writelane_b32 v253, s0, 12
	v_mov_b32_e32 v236, 0x2000
	v_mov_b32_e32 v237, 1
	v_writelane_b32 v253, s1, 13
	s_add_u32 s0, s78, 0xdd00000
	s_addc_u32 s1, s79, 0
	v_writelane_b32 v253, s0, 14
	v_mov_b32_e32 v239, 0x9000
	v_mov_b32_e32 v245, 0x3e000000
	v_writelane_b32 v253, s1, 15
	s_add_u32 s0, s78, 0xde00000
	s_addc_u32 s1, s79, 0
	v_writelane_b32 v253, s0, 16
	s_movk_i32 s65, 0x88
	s_mov_b32 s95, 0x20000
	v_writelane_b32 v253, s1, 17
	s_add_u32 s0, s78, 0xda00000
	s_addc_u32 s1, s79, 0
	s_cmp_gt_i32 s33, 64
	v_writelane_b32 v253, s0, 18
	s_cselect_b32 s3, 64, 0
	s_ashr_i32 s29, s28, 31
	v_writelane_b32 v253, s1, 19
	s_sub_i32 s0, s33, s3
	s_lshl_b32 s1, s0, 3
	s_lshl_b32 s0, s0, 9
	v_writelane_b32 v253, s1, 20
	s_cmp_lt_i32 s2, 0
	v_writelane_b32 v253, s0, 21
	s_cselect_b64 s[0:1], -1, 0
	v_writelane_b32 v253, s0, 22
	s_mov_b32 s54, 0x9000
	s_movk_i32 s66, 0x1000
	v_writelane_b32 v253, s1, 23
	s_add_u32 s0, s78, 0x26400000
	v_writelane_b32 v253, s0, 24
	s_addc_u32 s0, s79, 0
	s_add_u32 s34, s78, 0x26400200
	s_addc_u32 s35, s79, 0
	s_add_u32 s36, s78, 0x26400400
	s_addc_u32 s37, s79, 0
	s_add_u32 s24, s78, 0x26400500
	s_addc_u32 s25, s79, 0
	s_add_u32 s16, s78, 0x26400600
	s_addc_u32 s17, s79, 0
	s_add_u32 s18, s78, 0x26400700
	s_addc_u32 s19, s79, 0
	s_add_u32 s20, s78, 0x26400800
	s_addc_u32 s21, s79, 0
	s_add_u32 s22, s78, 0x26400900
	s_addc_u32 s23, s79, 0
	s_add_u32 s42, s78, 0x26400a00
	s_addc_u32 s43, s79, 0
	s_add_u32 s46, s78, 0x26400b00
	s_addc_u32 s47, s79, 0
	s_add_u32 s48, s78, 0x26400c00
	s_addc_u32 s49, s79, 0
	s_add_u32 s60, s78, 0x26400d00
	s_addc_u32 s61, s79, 0
	s_add_u32 s62, s78, 0x26400e00
	s_addc_u32 s63, s79, 0
	s_add_u32 s72, s78, 0x26400f00
	s_addc_u32 s73, s79, 0
	s_add_u32 s82, s78, 0x26401000
	s_addc_u32 s83, s79, 0
	s_add_u32 s84, s78, 0x26401100
	s_addc_u32 s85, s79, 0
	s_add_u32 s86, s78, 0x26401200
	s_addc_u32 s87, s79, 0
	s_add_u32 s88, s78, 0x26401300
	s_addc_u32 s89, s79, 0
	v_writelane_b32 v253, s0, 25
	s_add_u32 s0, s78, 0x26403400
	s_addc_u32 s1, s79, 0
	v_writelane_b32 v253, s0, 26
	s_movk_i32 s69, 0x300
	s_movk_i32 s68, 0x2000
	v_writelane_b32 v253, s1, 27
	s_add_u32 s0, s78, 0x26403500
	s_addc_u32 s1, s79, 0
	s_abs_i32 s2, s33
	v_cvt_f32_u32_e32 v1, s2
	v_writelane_b32 v253, s0, 28
	s_mov_b32 s59, 0x12000
	s_mov_b32 s67, 0x24000
	v_rcp_iflag_f32_e32 v1, v1
	v_writelane_b32 v253, s1, 29
	s_movk_i32 s0, 0x3ff
	v_and_or_b32 v0, v0, s0, v244
	v_mul_f32_e32 v1, 0x4f7ffffe, v1
	v_cvt_u32_f32_e32 v1, v1
	s_sub_i32 s0, 0, s2
	s_mov_b32 s81, 0x2081cea
	s_mov_b32 s74, 0x36000
	v_readfirstlane_b32 s1, v1
	s_mul_i32 s0, s0, s1
	s_mul_hi_u32 s0, s1, s0
	s_add_i32 s0, s1, s0
	v_writelane_b32 v253, s0, 30
	s_mul_hi_u32 s0, s0, 0x5c0
	s_mul_i32 s0, s0, s2
	s_sub_i32 s0, 0x5c0, s0
	s_sub_i32 s1, s0, s2
	s_cmp_ge_u32 s0, s2
	s_cselect_b32 s0, s1, s0
	s_sub_i32 s1, s0, s2
	s_cmp_ge_u32 s0, s2
	v_writelane_b32 v253, s2, 31
	s_cselect_b32 s0, s1, s0
	v_writelane_b32 v253, s0, 32
	s_lshl_b32 s0, s33, 12
	s_lshl_b32 s1, s3, 12
	v_writelane_b32 v253, s3, 33
	s_sub_i32 s0, s0, s1
	v_writelane_b32 v253, s0, 34
	s_mul_i32 s0, s33, 0x11000
	s_mul_hi_i32 s1, s28, 0x88
	v_writelane_b32 v253, s0, 35
	s_movk_i32 s2, 0x3000
	s_mov_b32 s3, 0x22000000
	v_writelane_b32 v253, s1, 36
	s_lshl_b32 s0, s33, 4
	v_writelane_b32 v253, s0, 37
	s_lshl_b32 s0, s33, 10
	v_writelane_b32 v253, s0, 38
	s_lshl_b32 s0, s33, 11
	v_writelane_b32 v253, s0, 39
	s_add_i32 s0, 0, 0x2020c
	v_writelane_b32 v253, s0, 40
	s_add_i32 s0, 0, 0x20208
	v_writelane_b32 v253, s0, 41
	s_add_i32 s0, 0, 0x20210
	v_writelane_b32 v253, s0, 42
	s_add_i32 s0, 0, 0x20000
	v_writelane_b32 v253, s0, 43
	s_add_i32 s0, 0, 0x20020
	v_writelane_b32 v253, s0, 44
	s_add_i32 s0, 0, 0x20080
	v_writelane_b32 v253, s0, 45
	s_add_i32 s0, 0, 0x20090
	v_writelane_b32 v253, s0, 46
	s_add_i32 s0, 0, 0x20048
	v_writelane_b32 v253, s0, 47
	s_add_i32 s0, 0, 0x20028
	v_writelane_b32 v253, s0, 48
	s_add_i32 s0, 0, 0x20008
	v_writelane_b32 v253, s0, 49
	s_add_i32 s0, 0, 0x20010
	v_writelane_b32 v253, s0, 50
	s_add_i32 s0, 0, 0x20018
	v_writelane_b32 v253, s0, 51
	s_add_i32 s0, 0, 0x20058
	v_writelane_b32 v253, s0, 52
	s_add_i32 s0, 0, 0x20068
	v_writelane_b32 v253, s0, 53
	s_add_i32 s0, 0, 0x20078
	v_writelane_b32 v253, s0, 54
	s_add_i32 s0, 0, 0x200a0
	v_writelane_b32 v253, s0, 55
	s_add_i32 s0, 0, 0x200b0
	v_writelane_b32 v253, s0, 56
	s_add_i32 s0, 0, 0x200c0
	v_writelane_b32 v253, s0, 57
	s_add_i32 s0, 0, 0x20098
	v_writelane_b32 v253, s0, 58
	s_add_i32 s0, 0, 0x20040
	v_writelane_b32 v253, s0, 59
	s_add_i32 s0, 0, 0x20038
	v_writelane_b32 v253, s0, 60
	s_add_i32 s0, 0, 0x20030
	v_writelane_b32 v253, s0, 61
	s_add_i32 s0, 0, 0x20200
	v_writelane_b32 v253, s0, 62
	s_add_i32 s0, 0, 0x20204
	v_writelane_b32 v253, s0, 63
	s_mov_b32 s75, 0x3f000
	v_readlane_b32 s0, v253, 0
	s_mov_b32 s52, s0
	s_mov_b32 s27, 0
	v_cmp_eq_u32_e64 s[0:1], 0, v0
	s_mov_b64 s[70:71], 0x200
	s_mov_b64 s[50:51], 0x80
	v_writelane_b32 v254, s0, 0
	s_nop 1
	v_writelane_b32 v254, s1, 1
	s_lshl_b64 s[0:1], s[28:29], 7
	v_writelane_b32 v254, s0, 2
	s_nop 1
	v_writelane_b32 v254, s1, 3
	s_lshl_b64 s[0:1], s[28:29], 6
	v_writelane_b32 v254, s0, 4
	s_nop 1
	v_writelane_b32 v254, s1, 5
	s_lshl_b64 s[0:1], s[28:29], 2
	v_writelane_b32 v254, s0, 6
	s_nop 1
	v_writelane_b32 v254, s1, 7
	s_lshl_b64 s[0:1], s[28:29], 1
	v_writelane_b32 v254, s0, 8
	s_nop 1
	v_writelane_b32 v254, s1, 9
	v_writelane_b32 v254, s28, 10
	s_nop 1
	v_writelane_b32 v254, s29, 11
	v_writelane_b32 v254, s30, 12
	s_nop 1
	v_writelane_b32 v254, s31, 13
	v_writelane_b32 v254, s34, 14
	s_nop 1
	v_writelane_b32 v254, s35, 15
	v_writelane_b32 v254, s36, 16
	s_nop 1
	v_writelane_b32 v254, s37, 17
	v_writelane_b32 v254, s24, 18
	s_nop 1
	v_writelane_b32 v254, s25, 19
	v_writelane_b32 v254, s16, 20
	s_nop 1
	v_writelane_b32 v254, s17, 21
	v_writelane_b32 v254, s18, 22
	s_nop 1
	v_writelane_b32 v254, s19, 23
	v_writelane_b32 v254, s20, 24
	s_nop 1
	v_writelane_b32 v254, s21, 25
	v_writelane_b32 v254, s22, 26
	s_nop 1
	v_writelane_b32 v254, s23, 27
	v_writelane_b32 v254, s64, 28
	v_writelane_b32 v254, s26, 29
	v_writelane_b32 v254, s42, 30
	s_nop 1
	v_writelane_b32 v254, s43, 31
	v_writelane_b32 v254, s46, 32
	s_nop 1
	v_writelane_b32 v254, s47, 33
	v_writelane_b32 v254, s48, 34
	s_nop 1
	v_writelane_b32 v254, s49, 35
	v_writelane_b32 v254, s60, 36
	s_nop 1
	v_writelane_b32 v254, s61, 37
	v_writelane_b32 v254, s62, 38
	s_nop 1
	v_writelane_b32 v254, s63, 39
	v_writelane_b32 v254, s72, 40
	s_nop 1
	v_writelane_b32 v254, s73, 41
	v_writelane_b32 v254, s82, 42
	s_nop 1
	v_writelane_b32 v254, s83, 43
	v_writelane_b32 v254, s84, 44
	s_nop 1
	v_writelane_b32 v254, s85, 45
	v_writelane_b32 v254, s86, 46
	s_nop 1
	v_writelane_b32 v254, s87, 47
	v_writelane_b32 v254, s88, 48
	s_nop 1
	v_writelane_b32 v254, s89, 49
	s_mov_b32 s99, 0
	s_mov_b32 s100, 0
	s_branch .LBB0_13

.LBB0_784:
	s_getreg_b32 s6, hwreg(HW_REG_XCC_ID, 0, 4)
	s_waitcnt vmcnt(0)
	s_waitcnt vmcnt(0) lgkmcnt(0)
	s_barrier
	s_mov_b64 s[4:5], exec
	v_readlane_b32 s8, v253, 3
	v_readlane_b32 s9, v253, 4
	s_and_b64 s[8:9], s[4:5], s[8:9]
	s_mov_b64 exec, s[8:9]
	s_cbranch_execz .LBB0_11
	s_cmp_eq_u32 s99, 0
	s_cbranch_scc1 .Lfb_global
	s_add_i32 s10, s44, -3
	s_cmp_lt_i32 s10, 0
	s_cbranch_scc1 .Lfb_global
	s_mul_i32 s11, s10, 47
	s_lshr_b32 s11, s11, 9
	s_mul_i32 s11, s11, 11
	s_sub_i32 s10, s10, s11
	s_lshl_b32 s10, 1, s10
	s_and_b32 s10, s10, 0x3e7
	s_cmp_eq_u32 s10, 0
	s_cbranch_scc1 .Lfb_global
	v_readlane_b32 s7, v253, 40
	v_readlane_b32 s10, v253, 24
	v_readlane_b32 s11, v253, 25
	s_add_i32 s100, s100, 1
	s_and_b32 s12, s6, 15
	s_lshl_b32 s8, s12, 8
	s_add_u32 s8, s10, s8
	s_addc_u32 s9, s11, 0
	s_add_u32 s8, s8, 0x1480
	s_addc_u32 s9, s9, 0
	v_mov_b32_e32 v0, s7
	ds_read_b32 v0, v0
	v_mov_b32_e32 v2, s100
	s_waitcnt lgkmcnt(0)
	v_lshlrev_b32_e32 v1, 2, v0
	global_store_dword v1, v2, s[8:9] sc0 sc1
	s_mov_b32 exec_lo, -1
	s_mov_b32 exec_hi, 0
	v_mbcnt_lo_u32_b32 v3, -1, 0
	v_lshlrev_b32_e32 v3, 2, v3
	s_mov_b32 s10, 0
.Lfb_poll:
	global_load_dword v4, v3, s[8:9] sc1
	s_add_i32 s10, s10, 1
	s_waitcnt vmcnt(0)
	v_cmp_le_u32_e32 vcc, s100, v4
	s_nop 1
	s_cmp_eq_u64 vcc, exec
	s_cbranch_scc1 .Lfb_done
	s_cmp_lt_u32 s10, 0x400000
	s_cbranch_scc1 .Lfb_poll
.Lfb_done:
	buffer_inv sc1
	s_waitcnt vmcnt(0)
	s_branch .LBB0_11
.Lfb_global:
	v_readlane_b32 s7, v253, 62
	s_waitcnt vmcnt(0) expcnt(0) lgkmcnt(0)
	s_and_b32 s12, s6, 15
	v_mov_b32_e32 v0, s7
	ds_read_b32 v2, v0
	v_readlane_b32 s7, v253, 63
	s_waitcnt lgkmcnt(0)
	v_cmp_ne_u32_e32 vcc, 0, v2
	v_mov_b32_e32 v0, s7
	ds_read_b32 v0, v0
	s_cbranch_vccnz .LBB0_800
	v_readlane_b32 s8, v253, 1
	v_readlane_b32 s9, v253, 2
	s_load_dwordx2 s[6:7], s[8:9], 0x4
	s_mov_b32 s14, 1
	s_waitcnt lgkmcnt(0)
	s_mul_i32 s13, s6, s33
	s_mul_i32 s13, s13, s7
	s_branch .LBB0_788

.LBB0_816:
	s_andn2_saveexec_b64 s[8:9], s[8:9]
	s_cbranch_execz .LBB0_11
	s_mov_b64 s[8:9], exec
	s_cmp_eq_u32 s99, 0
	s_cbranch_scc1 .Lxb_global
	s_add_i32 s10, s44, -3
	s_cmp_lt_i32 s10, 0
	s_cbranch_scc1 .Lxb_global
	s_mul_i32 s11, s10, 47
	s_lshr_b32 s11, s11, 9
	s_mul_i32 s11, s11, 11
	s_sub_i32 s10, s10, s11
	s_lshl_b32 s10, 1, s10
	s_and_b32 s10, s10, 0x0
	s_cmp_lg_u32 s10, 0
	s_cbranch_scc1 .LBB0_833

	.amdhsa_kernel _Z4mega4Args
		.amdhsa_group_segment_fixed_size 0
		.amdhsa_private_segment_fixed_size 0
		.amdhsa_kernarg_size 488
		.amdhsa_user_sgpr_count 2
		.amdhsa_user_sgpr_dispatch_ptr 0
		.amdhsa_user_sgpr_queue_ptr 0
		.amdhsa_user_sgpr_kernarg_segment_ptr 1
		.amdhsa_user_sgpr_dispatch_id 0
		.amdhsa_user_sgpr_kernarg_preload_length 0
		.amdhsa_user_sgpr_kernarg_preload_offset 0
		.amdhsa_user_sgpr_private_segment_size 0
		.amdhsa_uses_dynamic_stack 0
		.amdhsa_enable_private_segment 0
		.amdhsa_system_sgpr_workgroup_id_x 1
		.amdhsa_system_sgpr_workgroup_id_y 0
		.amdhsa_system_sgpr_workgroup_id_z 0
		.amdhsa_system_sgpr_workgroup_info 0
		.amdhsa_system_vgpr_workitem_id 2
		.amdhsa_next_free_vgpr 256
		.amdhsa_next_free_sgpr 102
		.amdhsa_accum_offset 256
		.amdhsa_reserve_vcc 1
		.amdhsa_float_round_mode_32 0
		.amdhsa_float_round_mode_16_64 0
		.amdhsa_float_denorm_mode_32 3
		.amdhsa_float_denorm_mode_16_64 3
		.amdhsa_dx10_clamp 1
		.amdhsa_ieee_mode 1
		.amdhsa_fp16_overflow 0
		.amdhsa_tg_split 0
		.amdhsa_exception_fp_ieee_invalid_op 0
		.amdhsa_exception_fp_denorm_src 0
		.amdhsa_exception_fp_ieee_div_zero 0
		.amdhsa_exception_fp_ieee_overflow 0
		.amdhsa_exception_fp_ieee_underflow 0
		.amdhsa_exception_fp_ieee_inexact 0
		.amdhsa_exception_int_div_zero 0
	.end_amdhsa_kernel

amdhsa.kernels:
  - .agpr_count:     0
    .args:
      - .offset:         0
        .size:           232
        .value_kind:     by_value
      - .offset:         232
        .size:           4
        .value_kind:     hidden_block_count_x
      - .offset:         236
        .size:           4
        .value_kind:     hidden_block_count_y
      - .offset:         240
        .size:           4
        .value_kind:     hidden_block_count_z
      - .offset:         244
        .size:           2
        .value_kind:     hidden_group_size_x
      - .offset:         246
        .size:           2
        .value_kind:     hidden_group_size_y
      - .offset:         248
        .size:           2
        .value_kind:     hidden_group_size_z
      - .offset:         250
        .size:           2
        .value_kind:     hidden_remainder_x
      - .offset:         252
        .size:           2
        .value_kind:     hidden_remainder_y
      - .offset:         254
        .size:           2
        .value_kind:     hidden_remainder_z
      - .offset:         272
        .size:           8
        .value_kind:     hidden_global_offset_x
      - .offset:         280
        .size:           8
        .value_kind:     hidden_global_offset_y
      - .offset:         288
        .size:           8
        .value_kind:     hidden_global_offset_z
      - .offset:         296
        .size:           2
        .value_kind:     hidden_grid_dims
      - .offset:         320
        .size:           8
        .value_kind:     hidden_multigrid_sync_arg
      - .offset:         352
        .size:           4
        .value_kind:     hidden_dynamic_lds_size
    .group_segment_fixed_size: 0
    .kernarg_segment_align: 8
    .kernarg_segment_size: 488
    .language:       OpenCL C
    .language_version:
      - 2
      - 0
    .max_flat_workgroup_size: 512
    .name:           _Z4mega4Args
    .private_segment_fixed_size: 0
    .sgpr_count:     108
    .sgpr_spill_count: 169
    .symbol:         _Z4mega4Args.kd
    .uniform_work_group_size: 1
    .uses_dynamic_stack: false
    .vgpr_count:     256
    .vgpr_spill_count: 0
    .wavefront_size: 64
